# E1 L0: wave column remap (64wc+32bj) + mode-0 epilogue rewritten with in-wave LDS transpose for full 128B-line stores
# speedup vs baseline: 1.0122x; 1.0052x over previous
; #define PG8_STAGE(bufoff, gbase, voff) do { _Pragma("unroll") for (int _i = 0; _i < 2; ++_i) \
;         __builtin_amdgcn_global_load_lds((const unsigned*)((const char*)(gbase) + (voff)[_i]), (LAS unsigned*)(lds + (bufoff) + ldsw + _i * 8192), 16, 0, 0); } while (0)
; #define PG8_WAIT_V(n) asm volatile("s_waitcnt vmcnt(" #n ")" ::: "memory")
; #define PG8_BAR __builtin_amdgcn_s_barrier()
; template <class Epi, class Sched>
; __device__ __forceinline__ void gemm_phase(LAS unsigned char* lds, const int K, const int lda, const int ldb, const Sched& S, const Epi& E) {
;     int tid = threadIdx.x; asm volatile("" : "+v"(tid));
;     const int wid = __builtin_amdgcn_readfirstlane(tid >> 6), lane = tid & 63, wr = wid >> 2, wc = wid & 3, fr = lane & 15, fq = lane >> 4;
;     const int nt = K / BK;
;     unsigned voffA[2], voffB[2];
; #pragma unroll
;     for (int i = 0; i < 2; ++i) { int R, C; stage_rc(tid * 16 + i * 8192, R, C); const int Rb = (R & ~31) + perm32(R & 31);
;         voffA[i] = (unsigned)(R * lda + C) * 2u; voffB[i] = (unsigned)(Rb * ldb + C) * 2u; }
;     const size_t kstep = (size_t)(BK * 2);
;     const size_t hA = (size_t)HALF * lda * 2, hB = (size_t)HALF * ldb * 2;
;     const unsigned ldsw = (unsigned)wid * 1024u;
;     const int aoff = lds_byte(wr * 64 + fr, fq * 8), boff = lds_byte(wc * 32 + fr, fq * 8);
;     ...
;     Unit cur, nxt; int ui = 0;
;     if (!S.next(0, cur)) return;
;     f32x4 acc[2][2][4][2];
; #pragma unroll
;     for (int a = 0; a < 2; ++a)
; #pragma unroll
;         for (int b = 0; b < 2; ++b)
; #pragma unroll
;             for (int m = 0; m < 4; ++m)
; #pragma unroll
;                 for (int n = 0; n < 2; ++n) acc[a][b][m][n] = (f32x4){0.f, 0.f, 0.f, 0.f};
;     bf16x8 At[4][2], B0[2][2], B1[2][2];
;     const char* cA = S.aptr(cur); const char* cB = S.bptr(cur);
;     PG8_STAGE(PG8_SB(0, 0), cB, voffB); PG8_STAGE(PG8_SB(0, 1), cB + hB, voffB); PG8_STAGE(PG8_SA(0, 0), cA, voffA); PG8_STAGE(PG8_SA(0, 1), cA + hA, voffA);
;     if (wr == 1) PG8_BAR;
;     PG8_WAIT_V(2); PG8_BAR;
;     PG8_STAGE(PG8_SB(1, 0), cB + kstep, voffB); PG8_STAGE(PG8_SA(1, 0), cA + kstep, voffA); PG8_STAGE(PG8_SB(1, 1), cB + hB + kstep, voffB);
;     PG8_WAIT_V(6); PG8_BAR;
.LBB0_203:
	v_and_b32_e32 v157, 15, v10
	v_and_b32_e32 v17, 48, v10
	v_lshlrev_b32_e32 v18, 2, v10
	s_mov_b64 s[22:23], 0x80
	s_sext_i32_i16 s0, s4
	s_and_b32 s4, s18, 3
	s_lshl_b32 s7, s19, 13
	v_lshl_or_b32 v17, v157, 6, v17
	v_and_b32_e32 v18, 32, v18
	s_add_i32 m0, s1, 0x18000
	v_lshl_add_u64 v[6:7], v[6:7], 0, s[22:23]
	s_lshl_b32 s35, s19, 6
	v_bitop3_b32 v19, v17, s7, v18 bitop3:0xde
	s_lshl_b32 s7, s4, 5
	s_lshl_b32 s19, s4, 13
	s_waitcnt vmcnt(2)
	s_barrier
	global_load_lds_dwordx4 v[6:7], off
	v_lshl_add_u64 v[4:5], v[4:5], 0, s[22:23]
	s_add_i32 m0, s1, 0x1a000
	s_add_i32 s38, s1, 0x8000
	s_add_i32 s39, s1, 0xa000
	global_load_lds_dwordx4 v[4:5], off
	v_lshl_add_u64 v[0:1], v[0:1], 0, s[22:23]
	s_mov_b32 m0, s38
	s_add_u32 s24, s54, 0x80080
	global_load_lds_dwordx4 v[0:1], off
	v_lshl_add_u64 v[0:1], v[2:3], 0, s[22:23]
	s_mov_b32 m0, s39
	s_addc_u32 s25, s55, 0
	global_load_lds_dwordx4 v[0:1], off
	s_add_i32 m0, s1, 0x1c000
	v_lshl_add_u64 v[0:1], s[24:25], 0, v[132:133]
	global_load_lds_dwordx4 v[0:1], off
	v_lshl_add_u64 v[0:1], s[24:25], 0, v[128:129]
	s_add_i32 m0, s1, 0x1e000
	s_cmpk_lt_u32 s5, 0x100
	global_load_lds_dwordx4 v[0:1], off
	v_lshlrev_b32_e32 v26, 15, v8
	s_cselect_b64 s[24:25], -1, 0
	s_lshl_b32 s5, s18, 12
	v_and_b32_e32 v26, 0xffff0000, v26
	s_add_i32 s5, s5, 0
	v_lshl_add_u32 v9, v9, 12, v26
	v_and_b32_e32 v8, 1, v8
	s_add_i32 s5, s5, 0x20000
	v_lshl_or_b32 v8, v8, 6, v9
	s_add_u32 s41, s36, 0x1ce00000
	v_lshlrev_b32_e32 v0, 1, v10
	v_lshl_add_u32 v138, v11, 1, v8
	v_lshlrev_b32_e32 v8, 15, v13
	v_bfe_u32 v15, v10, 4, 2
	s_addc_u32 s62, s37, 0
	v_and_b32_e32 v0, 14, v0
	v_bfe_u32 v2, v10, 3, 1
	v_and_b32_e32 v8, 0xffff0000, v8
	s_add_u32 s63, s36, 0x14e00000
	v_add_u32_e32 v0, s5, v0
	v_bitop3_b32 v4, v2, v15, 2 bitop3:0x36
	v_lshl_add_u32 v8, v12, 12, v8
	v_and_b32_e32 v9, 1, v13
	s_addc_u32 s64, s37, 0
	v_xor_b32_e32 v3, v2, v15
	v_lshl_add_u32 v5, v4, 4, v0
	v_bitop3_b32 v4, v2, v15, 4 bitop3:0x36
	v_bitop3_b32 v2, v2, v15, 6 bitop3:0x36
	v_lshl_or_b32 v8, v9, 6, v8
	v_and_b32_e32 v159, 63, v10
	v_lshlrev_b32_e32 v16, 3, v15
	s_add_u32 s65, s36, 0xae00000
	v_lshlrev_b32_e32 v1, 10, v15
	v_lshl_add_u32 v15, v2, 4, v0
	v_and_b32_e32 v2, 7, v10
	v_bfe_u32 v10, v10, 3, 3
	v_lshl_add_u32 v140, v14, 1, v8
	v_mbcnt_lo_u32_b32 v8, -1, 0
	v_bitop3_b32 v161, v17, s19, v18 bitop3:0xde
	s_waitcnt vmcnt(6)
	s_addc_u32 s66, s37, 0
	s_lshl_b32 s4, s4, 21
	v_lshl_add_u32 v3, v3, 4, v0
	v_lshl_add_u32 v7, v4, 4, v0
	v_lshlrev_b32_e32 v0, 3, v2
	v_lshl_add_u32 v17, v10, 7, s5
	v_lshlrev_b32_e32 v18, 4, v2
	v_lshlrev_b32_e32 v2, 15, v10
	v_or_b32_e32 v4, 8, v10
	v_or_b32_e32 v6, 16, v10
	v_or_b32_e32 v10, 24, v10
	v_mbcnt_hi_u32_b32 v8, -1, v8
	v_lshl_add_u32 v20, v4, 7, s5
	v_xor_b32_e32 v21, 16, v18
	v_lshlrev_b32_e32 v4, 15, v4
	v_lshl_add_u32 v22, v6, 7, s5
	v_xor_b32_e32 v23, 32, v18
	v_lshlrev_b32_e32 v6, 15, v6
	v_lshl_add_u32 v24, v10, 7, s5
	v_xor_b32_e32 v25, 48, v18
	v_lshlrev_b32_e32 v10, 15, v10
	s_or_b32 s5, s4, 0x100000
	s_add_i32 s68, 0, 0x10000
	s_add_i32 s69, 0, 0x14000
	v_and_or_b32 v8, v8, 64, v157
	s_mov_b32 s21, 0
	s_ashr_i32 s67, s3, 31
	v_mov_b32_e32 v139, v137
	v_mov_b32_e32 v141, v137
	s_mov_b64 s[26:27], 0x100
	v_add_u32_e32 v163, 0, v19
	v_lshlrev_b32_e32 v165, 2, v8
	s_mov_b32 s28, 0x3a000000
	s_mov_b32 s70, 0x800000
	v_lshlrev_b32_e32 v136, 1, v0
	v_add_u32_e32 v167, v3, v1
	v_add_u32_e32 v169, v5, v1
	v_add_u32_e32 v171, v7, v1
	v_add_u32_e32 v173, v15, v1
	s_lshl_b32 s42, s4, 1
	v_add_u32_e32 v184, v17, v18
	v_lshlrev_b32_e32 v142, 1, v2
	v_add_u32_e32 v185, v20, v21
	v_lshlrev_b32_e32 v144, 1, v4
	v_add_u32_e32 v186, v22, v23
	v_lshlrev_b32_e32 v146, 1, v6
	v_add_u32_e32 v187, v24, v25
	v_lshlrev_b32_e32 v148, 1, v10
	s_lshl_b32 s44, s5, 1
	s_lshl_b32 s71, s7, 1
	v_lshlrev_b32_e32 v150, 1, v16
	v_mov_b64_e32 v[152:153], 0xa00
	v_mov_b64_e32 v[154:155], 0x9ff
	v_add_u32_e32 v188, s68, v161
	v_add_u32_e32 v189, 0x11000, v161
	v_mov_b32_e32 v156, 0x358637bd
	s_mov_b32 s72, 0
	s_barrier
	s_branch .LBB0_206

; #define PG8_STAGE(bufoff, gbase, voff) do { _Pragma("unroll") for (int _i = 0; _i < 2; ++_i) \
;         __builtin_amdgcn_global_load_lds((const unsigned*)((const char*)(gbase) + (voff)[_i]), (LAS unsigned*)(lds + (bufoff) + ldsw + _i * 8192), 16, 0, 0); } while (0)
; #define PG8_LDA(dst, b, h) do { _Pragma("unroll") for (int m = 0; m < 4; ++m) _Pragma("unroll") for (int k = 0; k < 2; ++k) dst[m][k] = *(const LAS bf16x8*)(lds + PG8_SA(b, h) + aoff + m * 2048 + k * 1024); } while (0)
; #define PG8_LDB(dst, b, h) do { _Pragma("unroll") for (int n = 0; n < 2; ++n) _Pragma("unroll") for (int k = 0; k < 2; ++k) dst[n][k] = *(const LAS bf16x8*)(lds + PG8_SB(b, h) + boff + n * 2048 + k * 1024); } while (0)
; #define PG8_MMA(ai, bj, At, Bt) do { __builtin_amdgcn_s_setprio(1); _Pragma("unroll") for (int m = 0; m < 4; ++m) _Pragma("unroll") for (int n = 0; n < 2; ++n) _Pragma("unroll") for (int k = 0; k < 2; ++k) \
;         acc[ai][bj][m][n] = __builtin_amdgcn_mfma_f32_16x16x32_bf16(Bt[n][k], At[m][k], acc[ai][bj][m][n], 0, 0, 0); __builtin_amdgcn_s_setprio(0); } while (0)
; #define PG8_WAIT_V(n) asm volatile("s_waitcnt vmcnt(" #n ")" ::: "memory")
; #define PG8_WAIT_L(n) asm volatile("s_waitcnt lgkmcnt(" #n ")" ::: "memory")
; #define PG8_BAR __builtin_amdgcn_s_barrier()
; #define PG8_SCHED __builtin_amdgcn_sched_barrier(0)
; template <class Epi, class Sched>
; __device__ __forceinline__ void gemm_phase(LAS unsigned char* lds, const int K, const int lda, const int ldb, const Sched& S, const Epi& E) {
;     ...
;             PG8_LDB(B0, 0, 0); PG8_LDB(B1, 0, 1); PG8_SCHED; PG8_LDA(At, 0, 0); PG8_STAGE(PG8_SA(1, 1), a1 + hA, voffA);
;             PG8_WAIT_V(8); PG8_WAIT_L(0); PG8_BAR; PG8_MMA(0, 0, At, B0); PG8_MMA(0, 1, At, B1); PG8_BAR; PG8_SCHED;
;             PG8_LDA(At, 0, 1); PG8_STAGE(PG8_SB(0, 0), b2, voffB); PG8_STAGE(PG8_SB(0, 1), b2 + hB, voffB); PG8_STAGE(PG8_SA(0, 0), a2, voffA);
;             PG8_WAIT_V(8); PG8_WAIT_L(0); PG8_BAR; PG8_MMA(1, 0, At, B0); PG8_MMA(1, 1, At, B1); PG8_BAR; PG8_SCHED;
.LBB0_209:
	ds_read_b128 v[174:177], v188
	ds_read_b128 v[178:181], v188 offset:1024
	ds_read_b128 v[190:193], v188 offset:2048
	ds_read_b128 v[194:197], v188 offset:3072
	ds_read_b128 v[198:201], v189
	ds_read_b128 v[202:205], v189 offset:1024
	ds_read_b128 v[206:209], v189 offset:2048
	ds_read_b128 v[210:213], v189 offset:3072
	s_add_u32 s49, s54, 0xfff80080
	s_addc_u32 s56, s55, -1
	s_cmp_eq_u32 s47, 28
	s_cselect_b32 s59, s7, s56
	s_cselect_b32 s58, s18, s49
	s_cselect_b32 s57, s19, s45
	s_cselect_b32 s56, s20, s43
	v_lshl_add_u64 v[182:183], s[54:55], 0, v[140:141]
	s_add_i32 m0, s1, 0xc000
	ds_read_b128 v[214:217], v163
	ds_read_b128 v[218:221], v163 offset:1024
	ds_read_b128 v[222:225], v163 offset:2048
	ds_read_b128 v[226:229], v163 offset:3072
	ds_read_b128 v[230:233], v163 offset:4096
	ds_read_b128 v[236:239], v163 offset:5120
	ds_read_b128 v[240:243], v163 offset:6144
	ds_read_b128 v[244:247], v163 offset:7168
	global_load_lds_dwordx4 v[182:183], off
	v_lshl_add_u64 v[182:183], s[54:55], 0, v[138:139]
	s_add_i32 m0, s1, 0xe000
	s_nop 0
	global_load_lds_dwordx4 v[182:183], off
	s_waitcnt vmcnt(8)
	s_waitcnt lgkmcnt(0)
	s_barrier
	s_setprio 1
	s_waitcnt lgkmcnt(0)
	v_mfma_f32_16x16x32_bf16 v[124:127], v[174:177], v[214:217], v[124:127]
	v_mfma_f32_16x16x32_bf16 v[120:123], v[190:193], v[214:217], v[120:123]
	v_mfma_f32_16x16x32_bf16 v[108:111], v[174:177], v[222:225], v[108:111]
	v_mfma_f32_16x16x32_bf16 v[104:107], v[190:193], v[222:225], v[104:107]
	v_mfma_f32_16x16x32_bf16 v[92:95], v[174:177], v[230:233], v[92:95]
	v_mfma_f32_16x16x32_bf16 v[88:91], v[190:193], v[230:233], v[88:91]
	v_mfma_f32_16x16x32_bf16 v[76:79], v[174:177], v[240:243], v[76:79]
	v_mfma_f32_16x16x32_bf16 v[72:75], v[190:193], v[240:243], v[72:75]
	v_mfma_f32_16x16x32_bf16 v[124:127], v[178:181], v[218:221], v[124:127]
	v_mfma_f32_16x16x32_bf16 v[120:123], v[194:197], v[218:221], v[120:123]
	v_mfma_f32_16x16x32_bf16 v[108:111], v[178:181], v[226:229], v[108:111]
	v_mfma_f32_16x16x32_bf16 v[104:107], v[194:197], v[226:229], v[104:107]
	v_mfma_f32_16x16x32_bf16 v[92:95], v[178:181], v[236:239], v[92:95]
	v_mfma_f32_16x16x32_bf16 v[88:91], v[194:197], v[236:239], v[88:91]
	v_mfma_f32_16x16x32_bf16 v[76:79], v[178:181], v[244:247], v[76:79]
	v_mfma_f32_16x16x32_bf16 v[72:75], v[194:197], v[244:247], v[72:75]
	s_setprio 0
	s_setprio 1
	v_mfma_f32_16x16x32_bf16 v[116:119], v[198:201], v[214:217], v[116:119]
	v_mfma_f32_16x16x32_bf16 v[112:115], v[206:209], v[214:217], v[112:115]
	v_mfma_f32_16x16x32_bf16 v[100:103], v[198:201], v[222:225], v[100:103]
	v_mfma_f32_16x16x32_bf16 v[96:99], v[206:209], v[222:225], v[96:99]
	v_mfma_f32_16x16x32_bf16 v[84:87], v[198:201], v[230:233], v[84:87]
	v_mfma_f32_16x16x32_bf16 v[80:83], v[206:209], v[230:233], v[80:83]
	v_mfma_f32_16x16x32_bf16 v[68:71], v[198:201], v[240:243], v[68:71]
	v_mfma_f32_16x16x32_bf16 v[64:67], v[206:209], v[240:243], v[64:67]
	v_mfma_f32_16x16x32_bf16 v[116:119], v[202:205], v[218:221], v[116:119]
	v_mfma_f32_16x16x32_bf16 v[112:115], v[210:213], v[218:221], v[112:115]
	v_mfma_f32_16x16x32_bf16 v[100:103], v[202:205], v[226:229], v[100:103]
	v_mfma_f32_16x16x32_bf16 v[96:99], v[210:213], v[226:229], v[96:99]
	v_mfma_f32_16x16x32_bf16 v[84:87], v[202:205], v[236:239], v[84:87]
	v_mfma_f32_16x16x32_bf16 v[80:83], v[210:213], v[236:239], v[80:83]
	v_mfma_f32_16x16x32_bf16 v[68:71], v[202:205], v[244:247], v[68:71]
	v_mfma_f32_16x16x32_bf16 v[64:67], v[210:213], v[244:247], v[64:67]
	s_setprio 0
	s_barrier
	s_add_i32 s49, s68, s2
	v_lshl_add_u64 v[182:183], s[56:57], 0, v[132:133]
	s_mov_b32 m0, s49
	ds_read_b128 v[214:217], v163 offset:16384
	ds_read_b128 v[218:221], v163 offset:17408
	ds_read_b128 v[222:225], v163 offset:18432
	ds_read_b128 v[226:229], v163 offset:19456
	ds_read_b128 v[230:233], v163 offset:20480
	ds_read_b128 v[236:239], v163 offset:21504
	ds_read_b128 v[240:243], v163 offset:22528
	ds_read_b128 v[244:247], v163 offset:23552
	global_load_lds_dwordx4 v[182:183], off
	s_add_i32 m0, s49, 0x2000
	s_add_u32 s60, s56, 0x80000
	v_lshl_add_u64 v[248:249], s[56:57], 0, v[128:129]
	s_addc_u32 s61, s57, 0
	s_add_i32 s49, s69, s2
	global_load_lds_dwordx4 v[248:249], off
	v_lshl_add_u64 v[250:251], s[60:61], 0, v[132:133]
	s_mov_b32 m0, s49
	v_lshl_add_u64 v[252:253], s[58:59], 0, v[130:131]
	global_load_lds_dwordx4 v[250:251], off
	v_lshl_add_u64 v[250:251], s[60:61], 0, v[128:129]
	s_add_i32 m0, s49, 0x2000
	s_nop 0
	global_load_lds_dwordx4 v[250:251], off
	v_lshl_add_u64 v[250:251], s[58:59], 0, v[134:135]
	s_mov_b32 m0, s1
	s_nop 0
	global_load_lds_dwordx4 v[250:251], off
	s_mov_b32 m0, s17
	s_nop 0
	global_load_lds_dwordx4 v[252:253], off
	s_waitcnt vmcnt(8)
	s_waitcnt lgkmcnt(0)
	s_barrier
; #define PG8_STAGE(bufoff, gbase, voff) do { _Pragma("unroll") for (int _i = 0; _i < 2; ++_i) \
;         __builtin_amdgcn_global_load_lds((const unsigned*)((const char*)(gbase) + (voff)[_i]), (LAS unsigned*)(lds + (bufoff) + ldsw + _i * 8192), 16, 0, 0); } while (0)
; #define PG8_LDA(dst, b, h) do { _Pragma("unroll") for (int m = 0; m < 4; ++m) _Pragma("unroll") for (int k = 0; k < 2; ++k) dst[m][k] = *(const LAS bf16x8*)(lds + PG8_SA(b, h) + aoff + m * 2048 + k * 1024); } while (0)
; #define PG8_LDB(dst, b, h) do { _Pragma("unroll") for (int n = 0; n < 2; ++n) _Pragma("unroll") for (int k = 0; k < 2; ++k) dst[n][k] = *(const LAS bf16x8*)(lds + PG8_SB(b, h) + boff + n * 2048 + k * 1024); } while (0)
; #define PG8_MMA(ai, bj, At, Bt) do { __builtin_amdgcn_s_setprio(1); _Pragma("unroll") for (int m = 0; m < 4; ++m) _Pragma("unroll") for (int n = 0; n < 2; ++n) _Pragma("unroll") for (int k = 0; k < 2; ++k) \
;         acc[ai][bj][m][n] = __builtin_amdgcn_mfma_f32_16x16x32_bf16(Bt[n][k], At[m][k], acc[ai][bj][m][n], 0, 0, 0); __builtin_amdgcn_s_setprio(0); } while (0)
; #define PG8_WAIT_V(n) asm volatile("s_waitcnt vmcnt(" #n ")" ::: "memory")
; #define PG8_WAIT_L(n) asm volatile("s_waitcnt lgkmcnt(" #n ")" ::: "memory")
; #define PG8_BAR __builtin_amdgcn_s_barrier()
; #define PG8_SCHED __builtin_amdgcn_sched_barrier(0)
; template <class Epi, class Sched>
; __device__ __forceinline__ void gemm_phase(LAS unsigned char* lds, const int K, const int lda, const int ldb, const Sched& S, const Epi& E) {
;     ...
;             PG8_WAIT_V(8); PG8_WAIT_L(0); PG8_BAR; PG8_MMA(1, 0, At, B0); PG8_MMA(1, 1, At, B1); PG8_BAR; PG8_SCHED;
;             PG8_LDB(B0, 1, 0); PG8_LDB(B1, 1, 1); PG8_SCHED; PG8_LDA(At, 1, 0); PG8_STAGE(PG8_SA(0, 1), a2 + hA, voffA);
;             PG8_WAIT_V(8); PG8_WAIT_L(0); PG8_BAR; PG8_MMA(0, 0, At, B0); PG8_MMA(0, 1, At, B1); PG8_BAR; PG8_SCHED;
;             PG8_LDA(At, 1, 1); PG8_STAGE(PG8_SB(1, 0), b3, voffB); PG8_STAGE(PG8_SB(1, 1), b3 + hB, voffB); PG8_STAGE(PG8_SA(1, 0), a3, voffA);
	s_setprio 1
	s_waitcnt lgkmcnt(0)
	v_mfma_f32_16x16x32_bf16 v[60:63], v[174:177], v[214:217], v[60:63]
	v_mfma_f32_16x16x32_bf16 v[56:59], v[190:193], v[214:217], v[56:59]
	v_mfma_f32_16x16x32_bf16 v[44:47], v[174:177], v[222:225], v[44:47]
	v_mfma_f32_16x16x32_bf16 v[40:43], v[190:193], v[222:225], v[40:43]
	v_mfma_f32_16x16x32_bf16 v[28:31], v[174:177], v[230:233], v[28:31]
	v_mfma_f32_16x16x32_bf16 v[24:27], v[190:193], v[230:233], v[24:27]
	v_mfma_f32_16x16x32_bf16 v[12:15], v[174:177], v[240:243], v[12:15]
	v_mfma_f32_16x16x32_bf16 v[8:11], v[190:193], v[240:243], v[8:11]
	v_mfma_f32_16x16x32_bf16 v[60:63], v[178:181], v[218:221], v[60:63]
	v_mfma_f32_16x16x32_bf16 v[56:59], v[194:197], v[218:221], v[56:59]
	v_mfma_f32_16x16x32_bf16 v[44:47], v[178:181], v[226:229], v[44:47]
	v_mfma_f32_16x16x32_bf16 v[40:43], v[194:197], v[226:229], v[40:43]
	v_mfma_f32_16x16x32_bf16 v[28:31], v[178:181], v[236:239], v[28:31]
	v_mfma_f32_16x16x32_bf16 v[24:27], v[194:197], v[236:239], v[24:27]
	v_mfma_f32_16x16x32_bf16 v[12:15], v[178:181], v[244:247], v[12:15]
	v_mfma_f32_16x16x32_bf16 v[8:11], v[194:197], v[244:247], v[8:11]
	s_setprio 0
	s_setprio 1
	v_mfma_f32_16x16x32_bf16 v[52:55], v[198:201], v[214:217], v[52:55]
	v_mfma_f32_16x16x32_bf16 v[48:51], v[206:209], v[214:217], v[48:51]
	v_mfma_f32_16x16x32_bf16 v[36:39], v[198:201], v[222:225], v[36:39]
	v_mfma_f32_16x16x32_bf16 v[32:35], v[206:209], v[222:225], v[32:35]
	v_mfma_f32_16x16x32_bf16 v[20:23], v[198:201], v[230:233], v[20:23]
	v_mfma_f32_16x16x32_bf16 v[16:19], v[206:209], v[230:233], v[16:19]
	v_mfma_f32_16x16x32_bf16 v[4:7], v[198:201], v[240:243], v[4:7]
	v_mfma_f32_16x16x32_bf16 v[0:3], v[206:209], v[240:243], v[0:3]
	v_mfma_f32_16x16x32_bf16 v[52:55], v[202:205], v[218:221], v[52:55]
	v_mfma_f32_16x16x32_bf16 v[48:51], v[210:213], v[218:221], v[48:51]
	v_mfma_f32_16x16x32_bf16 v[36:39], v[202:205], v[226:229], v[36:39]
	v_mfma_f32_16x16x32_bf16 v[32:35], v[210:213], v[226:229], v[32:35]
	v_mfma_f32_16x16x32_bf16 v[20:23], v[202:205], v[236:239], v[20:23]
	v_mfma_f32_16x16x32_bf16 v[16:19], v[210:213], v[236:239], v[16:19]
	v_mfma_f32_16x16x32_bf16 v[4:7], v[202:205], v[244:247], v[4:7]
	v_mfma_f32_16x16x32_bf16 v[0:3], v[210:213], v[244:247], v[0:3]
	s_setprio 0
	s_barrier
	s_add_i32 s49, 0, 0x18000
	v_add_u32_e32 v143, s49, v161
	s_add_i32 s60, 0, 0x1c000
	ds_read_b128 v[174:177], v143
	ds_read_b128 v[178:181], v143 offset:1024
	ds_read_b128 v[190:193], v143 offset:2048
	ds_read_b128 v[194:197], v143 offset:3072
	v_add_u32_e32 v143, 0x19000, v161
	ds_read_b128 v[198:201], v143
	ds_read_b128 v[202:205], v143 offset:1024
	ds_read_b128 v[206:209], v143 offset:2048
	ds_read_b128 v[210:213], v143 offset:3072
	s_add_u32 s58, s58, 0x80000
	s_addc_u32 s59, s59, 0
	s_mov_b32 m0, s29
	v_lshl_add_u64 v[234:235], s[58:59], 0, v[134:135]
	ds_read_b128 v[214:217], v163 offset:32768
	ds_read_b128 v[218:221], v163 offset:33792
	ds_read_b128 v[222:225], v163 offset:34816
	ds_read_b128 v[226:229], v163 offset:35840
	ds_read_b128 v[230:233], v163 offset:36864
	ds_read_b128 v[236:239], v163 offset:37888
	ds_read_b128 v[240:243], v163 offset:38912
	ds_read_b128 v[244:247], v163 offset:39936
	global_load_lds_dwordx4 v[234:235], off
	v_lshl_add_u64 v[234:235], s[58:59], 0, v[130:131]
	s_mov_b32 m0, s34
	s_nop 0
	global_load_lds_dwordx4 v[234:235], off
	s_waitcnt vmcnt(8)
	s_waitcnt lgkmcnt(0)
	s_barrier
	s_setprio 1
	s_waitcnt lgkmcnt(0)
	v_mfma_f32_16x16x32_bf16 v[124:127], v[174:177], v[214:217], v[124:127]
	v_mfma_f32_16x16x32_bf16 v[120:123], v[190:193], v[214:217], v[120:123]
	v_mfma_f32_16x16x32_bf16 v[108:111], v[174:177], v[222:225], v[108:111]
	v_mfma_f32_16x16x32_bf16 v[104:107], v[190:193], v[222:225], v[104:107]
	v_mfma_f32_16x16x32_bf16 v[92:95], v[174:177], v[230:233], v[92:95]
	v_mfma_f32_16x16x32_bf16 v[88:91], v[190:193], v[230:233], v[88:91]
	v_mfma_f32_16x16x32_bf16 v[76:79], v[174:177], v[240:243], v[76:79]
	v_mfma_f32_16x16x32_bf16 v[72:75], v[190:193], v[240:243], v[72:75]
	v_mfma_f32_16x16x32_bf16 v[124:127], v[178:181], v[218:221], v[124:127]
	v_mfma_f32_16x16x32_bf16 v[120:123], v[194:197], v[218:221], v[120:123]
	v_mfma_f32_16x16x32_bf16 v[108:111], v[178:181], v[226:229], v[108:111]
	v_mfma_f32_16x16x32_bf16 v[104:107], v[194:197], v[226:229], v[104:107]
	v_mfma_f32_16x16x32_bf16 v[92:95], v[178:181], v[236:239], v[92:95]
	v_mfma_f32_16x16x32_bf16 v[88:91], v[194:197], v[236:239], v[88:91]
	v_mfma_f32_16x16x32_bf16 v[76:79], v[178:181], v[244:247], v[76:79]
	v_mfma_f32_16x16x32_bf16 v[72:75], v[194:197], v[244:247], v[72:75]
	s_setprio 0
	s_setprio 1
	v_mfma_f32_16x16x32_bf16 v[116:119], v[198:201], v[214:217], v[116:119]
	v_mfma_f32_16x16x32_bf16 v[112:115], v[206:209], v[214:217], v[112:115]
	v_mfma_f32_16x16x32_bf16 v[100:103], v[198:201], v[222:225], v[100:103]
	v_mfma_f32_16x16x32_bf16 v[96:99], v[206:209], v[222:225], v[96:99]
	v_mfma_f32_16x16x32_bf16 v[84:87], v[198:201], v[230:233], v[84:87]
	v_mfma_f32_16x16x32_bf16 v[80:83], v[206:209], v[230:233], v[80:83]
	v_mfma_f32_16x16x32_bf16 v[68:71], v[198:201], v[240:243], v[68:71]
	v_mfma_f32_16x16x32_bf16 v[64:67], v[206:209], v[240:243], v[64:67]
	v_mfma_f32_16x16x32_bf16 v[116:119], v[202:205], v[218:221], v[116:119]
	v_mfma_f32_16x16x32_bf16 v[112:115], v[210:213], v[218:221], v[112:115]
	v_mfma_f32_16x16x32_bf16 v[100:103], v[202:205], v[226:229], v[100:103]
	v_mfma_f32_16x16x32_bf16 v[96:99], v[210:213], v[226:229], v[96:99]
	v_mfma_f32_16x16x32_bf16 v[84:87], v[202:205], v[236:239], v[84:87]
	v_mfma_f32_16x16x32_bf16 v[80:83], v[210:213], v[236:239], v[80:83]
	v_mfma_f32_16x16x32_bf16 v[68:71], v[202:205], v[244:247], v[68:71]
	v_mfma_f32_16x16x32_bf16 v[64:67], v[210:213], v[244:247], v[64:67]
	s_setprio 0
	s_barrier
; #define PG8_STAGE(bufoff, gbase, voff) do { _Pragma("unroll") for (int _i = 0; _i < 2; ++_i) \
;         __builtin_amdgcn_global_load_lds((const unsigned*)((const char*)(gbase) + (voff)[_i]), (LAS unsigned*)(lds + (bufoff) + ldsw + _i * 8192), 16, 0, 0); } while (0)
; #define PG8_LDA(dst, b, h) do { _Pragma("unroll") for (int m = 0; m < 4; ++m) _Pragma("unroll") for (int k = 0; k < 2; ++k) dst[m][k] = *(const LAS bf16x8*)(lds + PG8_SA(b, h) + aoff + m * 2048 + k * 1024); } while (0)
; #define PG8_MMA(ai, bj, At, Bt) do { __builtin_amdgcn_s_setprio(1); _Pragma("unroll") for (int m = 0; m < 4; ++m) _Pragma("unroll") for (int n = 0; n < 2; ++n) _Pragma("unroll") for (int k = 0; k < 2; ++k) \
;         acc[ai][bj][m][n] = __builtin_amdgcn_mfma_f32_16x16x32_bf16(Bt[n][k], At[m][k], acc[ai][bj][m][n], 0, 0, 0); __builtin_amdgcn_s_setprio(0); } while (0)
; #define PG8_WAIT_V(n) asm volatile("s_waitcnt vmcnt(" #n ")" ::: "memory")
; #define PG8_WAIT_L(n) asm volatile("s_waitcnt lgkmcnt(" #n ")" ::: "memory")
; #define PG8_BAR __builtin_amdgcn_s_barrier()
; #define PG8_SCHED __builtin_amdgcn_sched_barrier(0)
; template <class Epi, class Sched>
; __device__ __forceinline__ void gemm_phase(LAS unsigned char* lds, const int K, const int lda, const int ldb, const Sched& S, const Epi& E) {
;     ...
;             PG8_LDA(At, 1, 1); PG8_STAGE(PG8_SB(1, 0), b3, voffB); PG8_STAGE(PG8_SB(1, 1), b3 + hB, voffB); PG8_STAGE(PG8_SA(1, 0), a3, voffA);
;             PG8_WAIT_V(8); PG8_WAIT_L(0); PG8_BAR; PG8_MMA(1, 0, At, B0); PG8_MMA(1, 1, At, B1); PG8_BAR; PG8_SCHED;
;         }
;         if (wr == 0) PG8_BAR;
	s_add_i32 s49, s49, s2
	v_lshl_add_u64 v[182:183], v[182:183], 0, s[22:23]
	s_mov_b32 m0, s49
	ds_read_b128 v[214:217], v163 offset:49152
	ds_read_b128 v[218:221], v163 offset:50176
	ds_read_b128 v[222:225], v163 offset:51200
	ds_read_b128 v[226:229], v163 offset:52224
	ds_read_b128 v[230:233], v163 offset:53248
	ds_read_b128 v[236:239], v163 offset:54272
	ds_read_b128 v[240:243], v163 offset:55296
	ds_read_b128 v[244:247], v163 offset:56320
	global_load_lds_dwordx4 v[182:183], off
	s_add_i32 m0, s49, 0x2000
	s_add_u32 s56, s56, 0x80080
	v_lshl_add_u64 v[182:183], v[248:249], 0, s[22:23]
	s_addc_u32 s57, s57, 0
	s_add_i32 s49, s60, s2
	global_load_lds_dwordx4 v[182:183], off
	v_lshl_add_u64 v[182:183], s[56:57], 0, v[132:133]
	s_mov_b32 m0, s49
	s_nop 0
	global_load_lds_dwordx4 v[182:183], off
	v_lshl_add_u64 v[182:183], s[56:57], 0, v[128:129]
	s_add_i32 m0, s49, 0x2000
	s_nop 0
	global_load_lds_dwordx4 v[182:183], off
	v_lshl_add_u64 v[182:183], v[250:251], 0, s[22:23]
	s_mov_b32 m0, s38
	s_nop 0
	global_load_lds_dwordx4 v[182:183], off
	v_lshl_add_u64 v[182:183], v[252:253], 0, s[22:23]
	s_mov_b32 m0, s39
	s_nop 0
	global_load_lds_dwordx4 v[182:183], off
	s_waitcnt vmcnt(8)
	s_waitcnt lgkmcnt(0)
	s_barrier
	s_setprio 1
	s_waitcnt lgkmcnt(0)
	v_mfma_f32_16x16x32_bf16 v[60:63], v[174:177], v[214:217], v[60:63]
	v_mfma_f32_16x16x32_bf16 v[56:59], v[190:193], v[214:217], v[56:59]
	v_mfma_f32_16x16x32_bf16 v[44:47], v[174:177], v[222:225], v[44:47]
	v_mfma_f32_16x16x32_bf16 v[40:43], v[190:193], v[222:225], v[40:43]
	v_mfma_f32_16x16x32_bf16 v[28:31], v[174:177], v[230:233], v[28:31]
	v_mfma_f32_16x16x32_bf16 v[24:27], v[190:193], v[230:233], v[24:27]
	v_mfma_f32_16x16x32_bf16 v[12:15], v[174:177], v[240:243], v[12:15]
	v_mfma_f32_16x16x32_bf16 v[8:11], v[190:193], v[240:243], v[8:11]
	v_mfma_f32_16x16x32_bf16 v[60:63], v[178:181], v[218:221], v[60:63]
	v_mfma_f32_16x16x32_bf16 v[56:59], v[194:197], v[218:221], v[56:59]
	v_mfma_f32_16x16x32_bf16 v[44:47], v[178:181], v[226:229], v[44:47]
	v_mfma_f32_16x16x32_bf16 v[40:43], v[194:197], v[226:229], v[40:43]
	v_mfma_f32_16x16x32_bf16 v[28:31], v[178:181], v[236:239], v[28:31]
	v_mfma_f32_16x16x32_bf16 v[24:27], v[194:197], v[236:239], v[24:27]
	v_mfma_f32_16x16x32_bf16 v[12:15], v[178:181], v[244:247], v[12:15]
	v_mfma_f32_16x16x32_bf16 v[8:11], v[194:197], v[244:247], v[8:11]
	s_setprio 0
	s_setprio 1
	v_mfma_f32_16x16x32_bf16 v[52:55], v[198:201], v[214:217], v[52:55]
	v_mfma_f32_16x16x32_bf16 v[48:51], v[206:209], v[214:217], v[48:51]
	v_mfma_f32_16x16x32_bf16 v[36:39], v[198:201], v[222:225], v[36:39]
	v_mfma_f32_16x16x32_bf16 v[32:35], v[206:209], v[222:225], v[32:35]
	v_mfma_f32_16x16x32_bf16 v[20:23], v[198:201], v[230:233], v[20:23]
	v_mfma_f32_16x16x32_bf16 v[16:19], v[206:209], v[230:233], v[16:19]
	v_mfma_f32_16x16x32_bf16 v[4:7], v[198:201], v[240:243], v[4:7]
	v_mfma_f32_16x16x32_bf16 v[0:3], v[206:209], v[240:243], v[0:3]
	v_mfma_f32_16x16x32_bf16 v[52:55], v[202:205], v[218:221], v[52:55]
	v_mfma_f32_16x16x32_bf16 v[48:51], v[210:213], v[218:221], v[48:51]
	v_mfma_f32_16x16x32_bf16 v[36:39], v[202:205], v[226:229], v[36:39]
	v_mfma_f32_16x16x32_bf16 v[32:35], v[210:213], v[226:229], v[32:35]
	v_mfma_f32_16x16x32_bf16 v[20:23], v[202:205], v[236:239], v[20:23]
	v_mfma_f32_16x16x32_bf16 v[16:19], v[210:213], v[236:239], v[16:19]
	v_mfma_f32_16x16x32_bf16 v[4:7], v[202:205], v[244:247], v[4:7]
	v_mfma_f32_16x16x32_bf16 v[0:3], v[210:213], v[244:247], v[0:3]
	s_setprio 0
	s_barrier
	s_add_i32 s47, s47, 2
	s_add_u32 s43, s43, 0x100
	s_addc_u32 s45, s45, 0
	s_add_u32 s54, s54, 0x100
	s_addc_u32 s55, s55, 0
	s_cmp_gt_u32 s47, 29
	s_cbranch_scc0 .LBB0_209
	s_and_b64 vcc, exec, s[24:25]
	s_cbranch_vccz .LBB0_212
	s_barrier

; __device__ __forceinline__ unsigned cvt_pk_bf16(float lo, float hi) { unsigned r; asm("v_cvt_pk_bf16_f32 %0, %1, %2" : "=v"(r) : "v"(lo), "v"(hi)); return r; }
;     __device__ __forceinline__ void operator()(const f32x4 (&acc)[2][2][4][2], const Unit& u, int wr, int wc, int fr, int fq, LAS unsigned char* xs, int wid, int lane) const {
;     ...
;         if (mode == 0) {
; #pragma unroll
;             for (int ai = 0; ai < 2; ++ai)
; #pragma unroll
;                 for (int m = 0; m < 4; ++m) {
;                     const float r = rs[ai][m];
;                     bf16_t* rowp = base + (size_t)(row0 + ai * 128 + m * 16 + fr) * ldc + wc * 32 + 8 * fq;
; #pragma unroll
;                     for (int bj = 0; bj < 2; ++bj) { const f32x4 v0 = acc[ai][bj][m][0] * r, v1 = acc[ai][bj][m][1] * r;
;                         u32x4 w; w.x = cvt_pk_bf16(v0[0], v0[1]); w.y = cvt_pk_bf16(v0[2], v0[3]); w.z = cvt_pk_bf16(v1[0], v1[1]); w.w = cvt_pk_bf16(v1[2], v1[3]);
;                         *(u32x4*)(rowp + bj * 128) = w; }
;                     __builtin_amdgcn_sched_barrier(0);
;                 }
.LBB0_231:
	s_lshl_b32 s18, s6, 4
	s_mov_b32 s19, 0
	s_lshl_b32 s58, s6, 5
	s_mov_b32 s59, 0
	s_mul_i32 s60, s6, 0xa0
	s_mov_b32 s61, 0
	v_lshrrev_b32_e32 v174, 3, v159
	v_add_u32_e32 v174, s54, v174
	v_mul_lo_u32 v174, v174, s6
	v_and_b32_e32 v182, 7, v159
	v_lshlrev_b32_e32 v182, 4, v182
	v_lshl_add_u32 v174, v174, 1, v182
	v_lshlrev_b32_e32 v182, 1, v254
	v_and_b32_e32 v182, 0x180, v182
	v_add_u32_e32 v174, v174, v182
	v_mov_b32_e32 v175, 0
	v_lshl_add_u64 v[174:175], s[56:57], 0, v[174:175]
	v_and_b32_e32 v178, 0x1c0, v254
	v_lshlrev_b32_e32 v178, 6, v178
	v_add_u32_e32 v178, 0x20000, v178
	v_lshrrev_b32_e32 v179, 4, v159
	v_and_b32_e32 v182, 7, v157
	v_xor_b32_e32 v179, v179, v182
	v_lshlrev_b32_e32 v179, 4, v179
	v_lshl_add_u32 v179, v157, 7, v179
	v_add_u32_e32 v179, v178, v179
	v_xor_b32_e32 v180, 64, v179
	v_lshrrev_b32_e32 v181, 3, v159
	v_and_b32_e32 v182, 7, v159
	v_xor_b32_e32 v182, v182, v181
	v_lshlrev_b32_e32 v182, 4, v182
	v_lshl_add_u32 v181, v181, 7, v182
	v_add_u32_e32 v181, v178, v181
	s_waitcnt lgkmcnt(0)
	v_pk_mul_f32 v[124:125], v[124:125], v[172:173] op_sel_hi:[1,0]
	v_pk_mul_f32 v[126:127], v[126:127], v[172:173] op_sel_hi:[1,0]
	v_pk_mul_f32 v[120:121], v[120:121], v[172:173] op_sel_hi:[1,0]
	v_pk_mul_f32 v[122:123], v[122:123], v[172:173] op_sel_hi:[1,0]
	v_pk_mul_f32 v[116:117], v[116:117], v[172:173] op_sel_hi:[1,0]
	v_pk_mul_f32 v[118:119], v[118:119], v[172:173] op_sel_hi:[1,0]
	v_pk_mul_f32 v[112:113], v[112:113], v[172:173] op_sel_hi:[1,0]
	v_pk_mul_f32 v[114:115], v[114:115], v[172:173] op_sel_hi:[1,0]
	v_cvt_pk_bf16_f32 v192, v124, v125
	v_cvt_pk_bf16_f32 v193, v126, v127
	v_cvt_pk_bf16_f32 v194, v120, v121
	v_cvt_pk_bf16_f32 v195, v122, v123
	v_cvt_pk_bf16_f32 v196, v116, v117
	v_cvt_pk_bf16_f32 v197, v118, v119
	v_cvt_pk_bf16_f32 v198, v112, v113
	v_cvt_pk_bf16_f32 v199, v114, v115
	ds_write_b128 v179, v[192:195]
	ds_write_b128 v180, v[196:199]
	ds_read_b128 v[208:211], v181
	ds_read_b128 v[212:215], v181 offset:1024
	v_pk_mul_f32 v[108:109], v[108:109], v[170:171] op_sel_hi:[1,0]
	v_pk_mul_f32 v[110:111], v[110:111], v[170:171] op_sel_hi:[1,0]
	v_pk_mul_f32 v[104:105], v[104:105], v[170:171] op_sel_hi:[1,0]
	v_pk_mul_f32 v[106:107], v[106:107], v[170:171] op_sel_hi:[1,0]
	v_pk_mul_f32 v[100:101], v[100:101], v[170:171] op_sel_hi:[1,0]
	v_pk_mul_f32 v[102:103], v[102:103], v[170:171] op_sel_hi:[1,0]
	v_pk_mul_f32 v[96:97], v[96:97], v[170:171] op_sel_hi:[1,0]
	v_pk_mul_f32 v[98:99], v[98:99], v[170:171] op_sel_hi:[1,0]
	v_cvt_pk_bf16_f32 v200, v108, v109
	v_cvt_pk_bf16_f32 v201, v110, v111
	v_cvt_pk_bf16_f32 v202, v104, v105
	v_cvt_pk_bf16_f32 v203, v106, v107
	v_cvt_pk_bf16_f32 v204, v100, v101
	v_cvt_pk_bf16_f32 v205, v102, v103
	v_cvt_pk_bf16_f32 v206, v96, v97
	v_cvt_pk_bf16_f32 v207, v98, v99
	ds_write_b128 v179, v[200:203] offset:2048
	ds_write_b128 v180, v[204:207] offset:2048
	ds_read_b128 v[216:219], v181 offset:2048
	ds_read_b128 v[220:223], v181 offset:3072
	s_waitcnt lgkmcnt(4)
	v_lshl_add_u64 v[176:177], s[18:19], 0, v[174:175]
	global_store_dwordx4 v[174:175], v[208:211], off
	global_store_dwordx4 v[176:177], v[212:215], off
	v_lshl_add_u64 v[174:175], s[58:59], 0, v[174:175]
	v_pk_mul_f32 v[92:93], v[92:93], v[168:169] op_sel_hi:[1,0]
	v_pk_mul_f32 v[94:95], v[94:95], v[168:169] op_sel_hi:[1,0]
	v_pk_mul_f32 v[88:89], v[88:89], v[168:169] op_sel_hi:[1,0]
	v_pk_mul_f32 v[90:91], v[90:91], v[168:169] op_sel_hi:[1,0]
	v_pk_mul_f32 v[84:85], v[84:85], v[168:169] op_sel_hi:[1,0]
	v_pk_mul_f32 v[86:87], v[86:87], v[168:169] op_sel_hi:[1,0]
	v_pk_mul_f32 v[80:81], v[80:81], v[168:169] op_sel_hi:[1,0]
	v_pk_mul_f32 v[82:83], v[82:83], v[168:169] op_sel_hi:[1,0]
	v_cvt_pk_bf16_f32 v192, v92, v93
	v_cvt_pk_bf16_f32 v193, v94, v95
	v_cvt_pk_bf16_f32 v194, v88, v89
	v_cvt_pk_bf16_f32 v195, v90, v91
	v_cvt_pk_bf16_f32 v196, v84, v85
	v_cvt_pk_bf16_f32 v197, v86, v87
	v_cvt_pk_bf16_f32 v198, v80, v81
	v_cvt_pk_bf16_f32 v199, v82, v83
	ds_write_b128 v179, v[192:195]
	ds_write_b128 v180, v[196:199]
	ds_read_b128 v[208:211], v181
	ds_read_b128 v[212:215], v181 offset:1024
	s_waitcnt lgkmcnt(4)
	v_lshl_add_u64 v[176:177], s[18:19], 0, v[174:175]
	global_store_dwordx4 v[174:175], v[216:219], off
	global_store_dwordx4 v[176:177], v[220:223], off
	v_lshl_add_u64 v[174:175], s[58:59], 0, v[174:175]
	v_pk_mul_f32 v[76:77], v[76:77], v[166:167] op_sel_hi:[1,0]
	v_pk_mul_f32 v[78:79], v[78:79], v[166:167] op_sel_hi:[1,0]
	v_pk_mul_f32 v[72:73], v[72:73], v[166:167] op_sel_hi:[1,0]
	v_pk_mul_f32 v[74:75], v[74:75], v[166:167] op_sel_hi:[1,0]
	v_pk_mul_f32 v[68:69], v[68:69], v[166:167] op_sel_hi:[1,0]
	v_pk_mul_f32 v[70:71], v[70:71], v[166:167] op_sel_hi:[1,0]
	v_pk_mul_f32 v[64:65], v[64:65], v[166:167] op_sel_hi:[1,0]
	v_pk_mul_f32 v[66:67], v[66:67], v[166:167] op_sel_hi:[1,0]
	v_cvt_pk_bf16_f32 v200, v76, v77
	v_cvt_pk_bf16_f32 v201, v78, v79
	v_cvt_pk_bf16_f32 v202, v72, v73
	v_cvt_pk_bf16_f32 v203, v74, v75
	v_cvt_pk_bf16_f32 v204, v68, v69
	v_cvt_pk_bf16_f32 v205, v70, v71
	v_cvt_pk_bf16_f32 v206, v64, v65
	v_cvt_pk_bf16_f32 v207, v66, v67
	ds_write_b128 v179, v[200:203] offset:2048
	ds_write_b128 v180, v[204:207] offset:2048
	ds_read_b128 v[216:219], v181 offset:2048
	ds_read_b128 v[220:223], v181 offset:3072
	s_waitcnt lgkmcnt(4)
; __device__ __forceinline__ unsigned cvt_pk_bf16(float lo, float hi) { unsigned r; asm("v_cvt_pk_bf16_f32 %0, %1, %2" : "=v"(r) : "v"(lo), "v"(hi)); return r; }
;     __device__ __forceinline__ void operator()(const f32x4 (&acc)[2][2][4][2], const Unit& u, int wr, int wc, int fr, int fq, LAS unsigned char* xs, int wid, int lane) const {
;     ...
;         if (mode == 0) {
; #pragma unroll
;             for (int ai = 0; ai < 2; ++ai)
; #pragma unroll
;                 for (int m = 0; m < 4; ++m) {
;                     const float r = rs[ai][m];
;                     bf16_t* rowp = base + (size_t)(row0 + ai * 128 + m * 16 + fr) * ldc + wc * 32 + 8 * fq;
; #pragma unroll
;                     for (int bj = 0; bj < 2; ++bj) { const f32x4 v0 = acc[ai][bj][m][0] * r, v1 = acc[ai][bj][m][1] * r;
;                         u32x4 w; w.x = cvt_pk_bf16(v0[0], v0[1]); w.y = cvt_pk_bf16(v0[2], v0[3]); w.z = cvt_pk_bf16(v1[0], v1[1]); w.w = cvt_pk_bf16(v1[2], v1[3]);
;                         *(u32x4*)(rowp + bj * 128) = w; }
;                     __builtin_amdgcn_sched_barrier(0);
;                 }
	v_lshl_add_u64 v[176:177], s[18:19], 0, v[174:175]
	global_store_dwordx4 v[174:175], v[208:211], off
	global_store_dwordx4 v[176:177], v[212:215], off
	v_lshl_add_u64 v[174:175], s[58:59], 0, v[174:175]
	v_pk_mul_f32 v[60:61], v[60:61], v[164:165] op_sel_hi:[1,0]
	v_pk_mul_f32 v[62:63], v[62:63], v[164:165] op_sel_hi:[1,0]
	v_pk_mul_f32 v[56:57], v[56:57], v[164:165] op_sel_hi:[1,0]
	v_pk_mul_f32 v[58:59], v[58:59], v[164:165] op_sel_hi:[1,0]
	v_pk_mul_f32 v[52:53], v[52:53], v[164:165] op_sel_hi:[1,0]
	v_pk_mul_f32 v[54:55], v[54:55], v[164:165] op_sel_hi:[1,0]
	v_pk_mul_f32 v[48:49], v[48:49], v[164:165] op_sel_hi:[1,0]
	v_pk_mul_f32 v[50:51], v[50:51], v[164:165] op_sel_hi:[1,0]
	v_cvt_pk_bf16_f32 v192, v60, v61
	v_cvt_pk_bf16_f32 v193, v62, v63
	v_cvt_pk_bf16_f32 v194, v56, v57
	v_cvt_pk_bf16_f32 v195, v58, v59
	v_cvt_pk_bf16_f32 v196, v52, v53
	v_cvt_pk_bf16_f32 v197, v54, v55
	v_cvt_pk_bf16_f32 v198, v48, v49
	v_cvt_pk_bf16_f32 v199, v50, v51
	ds_write_b128 v179, v[192:195]
	ds_write_b128 v180, v[196:199]
	ds_read_b128 v[208:211], v181
	ds_read_b128 v[212:215], v181 offset:1024
	s_waitcnt lgkmcnt(4)
	v_lshl_add_u64 v[176:177], s[18:19], 0, v[174:175]
	global_store_dwordx4 v[174:175], v[216:219], off
	global_store_dwordx4 v[176:177], v[220:223], off
	v_lshl_add_u64 v[174:175], s[60:61], 0, v[174:175]
	v_pk_mul_f32 v[44:45], v[44:45], v[162:163] op_sel_hi:[1,0]
	v_pk_mul_f32 v[46:47], v[46:47], v[162:163] op_sel_hi:[1,0]
	v_pk_mul_f32 v[40:41], v[40:41], v[162:163] op_sel_hi:[1,0]
	v_pk_mul_f32 v[42:43], v[42:43], v[162:163] op_sel_hi:[1,0]
	v_pk_mul_f32 v[36:37], v[36:37], v[162:163] op_sel_hi:[1,0]
	v_pk_mul_f32 v[38:39], v[38:39], v[162:163] op_sel_hi:[1,0]
	v_pk_mul_f32 v[32:33], v[32:33], v[162:163] op_sel_hi:[1,0]
	v_pk_mul_f32 v[34:35], v[34:35], v[162:163] op_sel_hi:[1,0]
	v_cvt_pk_bf16_f32 v200, v44, v45
	v_cvt_pk_bf16_f32 v201, v46, v47
	v_cvt_pk_bf16_f32 v202, v40, v41
	v_cvt_pk_bf16_f32 v203, v42, v43
	v_cvt_pk_bf16_f32 v204, v36, v37
	v_cvt_pk_bf16_f32 v205, v38, v39
	v_cvt_pk_bf16_f32 v206, v32, v33
	v_cvt_pk_bf16_f32 v207, v34, v35
	ds_write_b128 v179, v[200:203] offset:2048
	ds_write_b128 v180, v[204:207] offset:2048
	ds_read_b128 v[216:219], v181 offset:2048
	ds_read_b128 v[220:223], v181 offset:3072
	s_waitcnt lgkmcnt(4)
	v_lshl_add_u64 v[176:177], s[18:19], 0, v[174:175]
	global_store_dwordx4 v[174:175], v[208:211], off
	global_store_dwordx4 v[176:177], v[212:215], off
	v_lshl_add_u64 v[174:175], s[58:59], 0, v[174:175]
	v_pk_mul_f32 v[28:29], v[28:29], v[160:161] op_sel_hi:[1,0]
	v_pk_mul_f32 v[30:31], v[30:31], v[160:161] op_sel_hi:[1,0]
	v_pk_mul_f32 v[24:25], v[24:25], v[160:161] op_sel_hi:[1,0]
	v_pk_mul_f32 v[26:27], v[26:27], v[160:161] op_sel_hi:[1,0]
	v_pk_mul_f32 v[20:21], v[20:21], v[160:161] op_sel_hi:[1,0]
	v_pk_mul_f32 v[22:23], v[22:23], v[160:161] op_sel_hi:[1,0]
	v_pk_mul_f32 v[16:17], v[16:17], v[160:161] op_sel_hi:[1,0]
	v_pk_mul_f32 v[18:19], v[18:19], v[160:161] op_sel_hi:[1,0]
	v_cvt_pk_bf16_f32 v192, v28, v29
	v_cvt_pk_bf16_f32 v193, v30, v31
	v_cvt_pk_bf16_f32 v194, v24, v25
	v_cvt_pk_bf16_f32 v195, v26, v27
	v_cvt_pk_bf16_f32 v196, v20, v21
	v_cvt_pk_bf16_f32 v197, v22, v23
	v_cvt_pk_bf16_f32 v198, v16, v17
	v_cvt_pk_bf16_f32 v199, v18, v19
	ds_write_b128 v179, v[192:195]
	ds_write_b128 v180, v[196:199]
	ds_read_b128 v[208:211], v181
	ds_read_b128 v[212:215], v181 offset:1024
	s_waitcnt lgkmcnt(4)
	v_lshl_add_u64 v[176:177], s[18:19], 0, v[174:175]
	global_store_dwordx4 v[174:175], v[216:219], off
	global_store_dwordx4 v[176:177], v[220:223], off
	v_lshl_add_u64 v[174:175], s[58:59], 0, v[174:175]
	v_pk_mul_f32 v[12:13], v[12:13], v[158:159] op_sel_hi:[1,0]
	v_pk_mul_f32 v[14:15], v[14:15], v[158:159] op_sel_hi:[1,0]
	v_pk_mul_f32 v[8:9], v[8:9], v[158:159] op_sel_hi:[1,0]
	v_pk_mul_f32 v[10:11], v[10:11], v[158:159] op_sel_hi:[1,0]
	v_pk_mul_f32 v[4:5], v[4:5], v[158:159] op_sel_hi:[1,0]
	v_pk_mul_f32 v[6:7], v[6:7], v[158:159] op_sel_hi:[1,0]
	v_pk_mul_f32 v[0:1], v[0:1], v[158:159] op_sel_hi:[1,0]
	v_pk_mul_f32 v[2:3], v[2:3], v[158:159] op_sel_hi:[1,0]
	v_cvt_pk_bf16_f32 v200, v12, v13
	v_cvt_pk_bf16_f32 v201, v14, v15
	v_cvt_pk_bf16_f32 v202, v8, v9
	v_cvt_pk_bf16_f32 v203, v10, v11
	v_cvt_pk_bf16_f32 v204, v4, v5
	v_cvt_pk_bf16_f32 v205, v6, v7
	v_cvt_pk_bf16_f32 v206, v0, v1
	v_cvt_pk_bf16_f32 v207, v2, v3
	ds_write_b128 v179, v[200:203] offset:2048
	ds_write_b128 v180, v[204:207] offset:2048
	ds_read_b128 v[216:219], v181 offset:2048
	ds_read_b128 v[220:223], v181 offset:3072
	s_waitcnt lgkmcnt(4)
	v_lshl_add_u64 v[176:177], s[18:19], 0, v[174:175]
	global_store_dwordx4 v[174:175], v[208:211], off
	global_store_dwordx4 v[176:177], v[212:215], off
	v_lshl_add_u64 v[174:175], s[58:59], 0, v[174:175]
	s_waitcnt lgkmcnt(0)
	v_lshl_add_u64 v[176:177], s[18:19], 0, v[174:175]
	global_store_dwordx4 v[174:175], v[216:219], off
	global_store_dwordx4 v[176:177], v[220:223], off
	s_andn2_b64 vcc, exec, s[4:5]
	s_mov_b64 s[4:5], -1
	s_cbranch_vccnz .LBB0_205
